# c16_mla_trg2_into_group0_buffers
# baseline (speedup 1.0000x reference)
.Lfm_odd_exp:
	v_sub_f32_e32 v96, v112, v236
	v_sub_f32_e32 v97, v113, v236
	ds_read_b64_tr_b16 v[112:113], v0 offset:0x200
	v_sub_f32_e32 v98, v114, v236
	v_sub_f32_e32 v99, v115, v236
	ds_read_b64_tr_b16 v[114:115], v0 offset:0xa00
	v_sub_f32_e32 v100, v116, v236
	v_sub_f32_e32 v101, v117, v236
	ds_read_b64_tr_b16 v[116:117], v0 offset:0x1200
	v_sub_f32_e32 v102, v118, v236
	v_sub_f32_e32 v103, v119, v236
	ds_read_b64_tr_b16 v[118:119], v0 offset:0x1a00
	v_sub_f32_e32 v104, v120, v236
	v_sub_f32_e32 v105, v121, v236
	ds_read_b64_tr_b16 v[120:121], v0 offset:0x2200
	v_sub_f32_e32 v106, v122, v236
	v_sub_f32_e32 v107, v123, v236
	ds_read_b64_tr_b16 v[122:123], v0 offset:0x2a00
	v_sub_f32_e32 v108, v124, v236
	v_sub_f32_e32 v109, v125, v236
	ds_read_b64_tr_b16 v[124:125], v0 offset:0x3200
	v_sub_f32_e32 v110, v126, v236
	v_sub_f32_e32 v111, v127, v236
	ds_read_b64_tr_b16 v[126:127], v0 offset:0x3a00
	v_sub_f32_e32 v80, v128, v236
	v_sub_f32_e32 v81, v129, v236
	v_sub_f32_e32 v82, v130, v236
	v_sub_f32_e32 v83, v131, v236
	s_waitcnt lgkmcnt(8)
	v_mfma_f32_32x32x16_bf16 v[64:79], v[192:195], v[208:211], v[64:79]
	v_exp_f32_e32 v96, v96
	v_exp_f32_e32 v80, v80
	v_sub_f32_e32 v84, v132, v236
	v_sub_f32_e32 v85, v133, v236
	v_mfma_f32_32x32x16_bf16 v[64:79], v[10:13], v[204:207], v[64:79]
	v_exp_f32_e32 v97, v97
	v_exp_f32_e32 v81, v81
	v_sub_f32_e32 v86, v134, v236
	v_sub_f32_e32 v87, v135, v236
	v_mfma_f32_32x32x16_bf16 v[64:79], v[6:9], v[200:203], v[64:79]
	v_exp_f32_e32 v98, v98
	v_exp_f32_e32 v82, v82
	v_sub_f32_e32 v88, v136, v236
	v_sub_f32_e32 v89, v137, v236
	v_mfma_f32_32x32x16_bf16 v[64:79], v[2:5], v[196:199], v[64:79]
	v_exp_f32_e32 v99, v99
	v_exp_f32_e32 v83, v83
	v_sub_f32_e32 v90, v138, v236
	v_sub_f32_e32 v91, v139, v236
	ds_read_b64_tr_b16 v[208:209], v0 offset:0x400
	ds_read_b64_tr_b16 v[210:211], v0 offset:0xc00
	ds_read_b64_tr_b16 v[204:205], v0 offset:0x1400
	ds_read_b64_tr_b16 v[206:207], v0 offset:0x1c00
	ds_read_b64_tr_b16 v[200:201], v0 offset:0x2400
	ds_read_b64_tr_b16 v[202:203], v0 offset:0x2c00
	ds_read_b64_tr_b16 v[196:197], v0 offset:0x3400
	ds_read_b64_tr_b16 v[198:199], v0 offset:0x3c00
	s_waitcnt lgkmcnt(8)
	v_mfma_f32_32x32x16_bf16 v[48:63], v[192:195], v[112:115], v[48:63]
	v_exp_f32_e32 v100, v100
	v_exp_f32_e32 v84, v84
	v_sub_f32_e32 v92, v140, v236
	v_mfma_f32_32x32x16_bf16 v[48:63], v[10:13], v[116:119], v[48:63]
	v_exp_f32_e32 v101, v101
	v_exp_f32_e32 v85, v85
	v_sub_f32_e32 v93, v141, v236
	v_mfma_f32_32x32x16_bf16 v[48:63], v[6:9], v[120:123], v[48:63]
	v_exp_f32_e32 v102, v102
	v_exp_f32_e32 v86, v86
	v_sub_f32_e32 v94, v142, v236
	v_mfma_f32_32x32x16_bf16 v[48:63], v[2:5], v[124:127], v[48:63]
	v_exp_f32_e32 v103, v103
	v_exp_f32_e32 v87, v87
	v_sub_f32_e32 v95, v143, v236
	ds_read_b64_tr_b16 v[112:113], v0 offset:0x600
	ds_read_b64_tr_b16 v[114:115], v0 offset:0xe00
	ds_read_b64_tr_b16 v[116:117], v0 offset:0x1600
	ds_read_b64_tr_b16 v[118:119], v0 offset:0x1e00
	ds_read_b64_tr_b16 v[120:121], v0 offset:0x2600
	ds_read_b64_tr_b16 v[122:123], v0 offset:0x2e00
	ds_read_b64_tr_b16 v[124:125], v0 offset:0x3600
	ds_read_b64_tr_b16 v[126:127], v0 offset:0x3e00
	s_waitcnt lgkmcnt(8)
	v_mfma_f32_32x32x16_bf16 v[32:47], v[192:195], v[208:211], v[32:47]
	v_exp_f32_e32 v104, v104
	v_exp_f32_e32 v88, v88
	v_mfma_f32_32x32x16_bf16 v[32:47], v[10:13], v[204:207], v[32:47]
	v_exp_f32_e32 v105, v105
	v_exp_f32_e32 v89, v89
	v_mfma_f32_32x32x16_bf16 v[32:47], v[6:9], v[200:203], v[32:47]
	v_exp_f32_e32 v106, v106
	v_exp_f32_e32 v90, v90
	v_mfma_f32_32x32x16_bf16 v[32:47], v[2:5], v[196:199], v[32:47]
	v_exp_f32_e32 v107, v107
	v_exp_f32_e32 v91, v91
	s_waitcnt lgkmcnt(0)
	v_mfma_f32_32x32x16_bf16 v[16:31], v[192:195], v[112:115], v[16:31]
	v_exp_f32_e32 v108, v108
	v_exp_f32_e32 v92, v92
	v_mfma_f32_32x32x16_bf16 v[16:31], v[10:13], v[116:119], v[16:31]
	v_exp_f32_e32 v109, v109
	v_exp_f32_e32 v93, v93
	v_mfma_f32_32x32x16_bf16 v[16:31], v[6:9], v[120:123], v[16:31]
	v_exp_f32_e32 v110, v110
	v_exp_f32_e32 v94, v94
	v_mfma_f32_32x32x16_bf16 v[16:31], v[2:5], v[124:127], v[16:31]
	v_exp_f32_e32 v111, v111
	v_exp_f32_e32 v95, v95
	v_cmp_gt_f32_e32 vcc, 1.0, v240
	s_cbranch_vccnz .Lresc_mla_odd_blk

.Lfm_even_exp:
	v_sub_f32_e32 v96, v112, v236
	v_sub_f32_e32 v97, v113, v236
	ds_read_b64_tr_b16 v[112:113], v243 offset:0x200
	v_sub_f32_e32 v98, v114, v236
	v_sub_f32_e32 v99, v115, v236
	ds_read_b64_tr_b16 v[114:115], v243 offset:0xa00
	v_sub_f32_e32 v100, v116, v236
	v_sub_f32_e32 v101, v117, v236
	ds_read_b64_tr_b16 v[116:117], v243 offset:0x1200
	v_sub_f32_e32 v102, v118, v236
	v_sub_f32_e32 v103, v119, v236
	ds_read_b64_tr_b16 v[118:119], v243 offset:0x1a00
	v_sub_f32_e32 v104, v120, v236
	v_sub_f32_e32 v105, v121, v236
	ds_read_b64_tr_b16 v[120:121], v243 offset:0x2200
	v_sub_f32_e32 v106, v122, v236
	v_sub_f32_e32 v107, v123, v236
	ds_read_b64_tr_b16 v[122:123], v243 offset:0x2a00
	v_sub_f32_e32 v108, v124, v236
	v_sub_f32_e32 v109, v125, v236
	ds_read_b64_tr_b16 v[124:125], v243 offset:0x3200
	v_sub_f32_e32 v110, v126, v236
	v_sub_f32_e32 v111, v127, v236
	ds_read_b64_tr_b16 v[126:127], v243 offset:0x3a00
	v_sub_f32_e32 v80, v128, v236
	v_sub_f32_e32 v81, v129, v236
	v_sub_f32_e32 v82, v130, v236
	v_sub_f32_e32 v83, v131, v236
	s_waitcnt lgkmcnt(8)
	v_mfma_f32_32x32x16_bf16 v[64:79], v[192:195], v[208:211], v[64:79]
	v_exp_f32_e32 v96, v96
	v_exp_f32_e32 v80, v80
	v_sub_f32_e32 v84, v132, v236
	v_sub_f32_e32 v85, v133, v236
	v_mfma_f32_32x32x16_bf16 v[64:79], v[10:13], v[204:207], v[64:79]
	v_exp_f32_e32 v97, v97
	v_exp_f32_e32 v81, v81
	v_sub_f32_e32 v86, v134, v236
	v_sub_f32_e32 v87, v135, v236
	v_mfma_f32_32x32x16_bf16 v[64:79], v[6:9], v[200:203], v[64:79]
	v_exp_f32_e32 v98, v98
	v_exp_f32_e32 v82, v82
	v_sub_f32_e32 v88, v136, v236
	v_sub_f32_e32 v89, v137, v236
	v_mfma_f32_32x32x16_bf16 v[64:79], v[2:5], v[196:199], v[64:79]
	v_exp_f32_e32 v99, v99
	v_exp_f32_e32 v83, v83
	v_sub_f32_e32 v90, v138, v236
	v_sub_f32_e32 v91, v139, v236
	ds_read_b64_tr_b16 v[208:209], v243 offset:0x400
	ds_read_b64_tr_b16 v[210:211], v243 offset:0xc00
	ds_read_b64_tr_b16 v[204:205], v243 offset:0x1400
	ds_read_b64_tr_b16 v[206:207], v243 offset:0x1c00
	ds_read_b64_tr_b16 v[200:201], v243 offset:0x2400
	ds_read_b64_tr_b16 v[202:203], v243 offset:0x2c00
	ds_read_b64_tr_b16 v[196:197], v243 offset:0x3400
	ds_read_b64_tr_b16 v[198:199], v243 offset:0x3c00
	s_waitcnt lgkmcnt(8)
	v_mfma_f32_32x32x16_bf16 v[48:63], v[192:195], v[112:115], v[48:63]
	v_exp_f32_e32 v100, v100
	v_exp_f32_e32 v84, v84
	v_sub_f32_e32 v92, v140, v236
	v_mfma_f32_32x32x16_bf16 v[48:63], v[10:13], v[116:119], v[48:63]
	v_exp_f32_e32 v101, v101
	v_exp_f32_e32 v85, v85
	v_sub_f32_e32 v93, v141, v236
	v_mfma_f32_32x32x16_bf16 v[48:63], v[6:9], v[120:123], v[48:63]
	v_exp_f32_e32 v102, v102
	v_exp_f32_e32 v86, v86
	v_sub_f32_e32 v94, v142, v236
	v_mfma_f32_32x32x16_bf16 v[48:63], v[2:5], v[124:127], v[48:63]
	v_exp_f32_e32 v103, v103
	v_exp_f32_e32 v87, v87
	v_sub_f32_e32 v95, v143, v236
	ds_read_b64_tr_b16 v[112:113], v243 offset:0x600
	ds_read_b64_tr_b16 v[114:115], v243 offset:0xe00
	ds_read_b64_tr_b16 v[116:117], v243 offset:0x1600
	ds_read_b64_tr_b16 v[118:119], v243 offset:0x1e00
	ds_read_b64_tr_b16 v[120:121], v243 offset:0x2600
	ds_read_b64_tr_b16 v[122:123], v243 offset:0x2e00
	ds_read_b64_tr_b16 v[124:125], v243 offset:0x3600
	ds_read_b64_tr_b16 v[126:127], v243 offset:0x3e00
	s_waitcnt lgkmcnt(8)
	v_mfma_f32_32x32x16_bf16 v[32:47], v[192:195], v[208:211], v[32:47]
	v_exp_f32_e32 v104, v104
	v_exp_f32_e32 v88, v88
	v_mfma_f32_32x32x16_bf16 v[32:47], v[10:13], v[204:207], v[32:47]
	v_exp_f32_e32 v105, v105
	v_exp_f32_e32 v89, v89
	v_mfma_f32_32x32x16_bf16 v[32:47], v[6:9], v[200:203], v[32:47]
	v_exp_f32_e32 v106, v106
	v_exp_f32_e32 v90, v90
	v_mfma_f32_32x32x16_bf16 v[32:47], v[2:5], v[196:199], v[32:47]
	v_exp_f32_e32 v107, v107
	v_exp_f32_e32 v91, v91
	s_waitcnt lgkmcnt(0)
	v_mfma_f32_32x32x16_bf16 v[16:31], v[192:195], v[112:115], v[16:31]
	v_exp_f32_e32 v108, v108
	v_exp_f32_e32 v92, v92
	v_mfma_f32_32x32x16_bf16 v[16:31], v[10:13], v[116:119], v[16:31]
	v_exp_f32_e32 v109, v109
	v_exp_f32_e32 v93, v93
	v_mfma_f32_32x32x16_bf16 v[16:31], v[6:9], v[120:123], v[16:31]
	v_exp_f32_e32 v110, v110
	v_exp_f32_e32 v94, v94
	v_mfma_f32_32x32x16_bf16 v[16:31], v[2:5], v[124:127], v[16:31]
	v_exp_f32_e32 v111, v111
	v_exp_f32_e32 v95, v95
	v_cmp_gt_f32_e32 vcc, 1.0, v0
	s_cbranch_vccnz .Lresc_mla_even_blk
